# speedup vs baseline: 1.0135x; 1.0135x over previous
; __device__ void phase_norm_final(const Params& p) {
;     ...
;     for (int row = (blockIdx.x * NWAVES + w) * 2; row < T; row += gridDim.x * NWAVES * 2) {
;         float4* xr = reinterpret_cast<float4*>(p.out + (size_t)row * D);
;         float4 v0[4], v1[4];
; #pragma unroll
;         for (int i = 0; i < 4; ++i) { v0[i] = xr[lane + 64 * i]; v1[i] = xr[256 + lane + 64 * i]; }
;         float ss0 = 0.f, ss1 = 0.f;
; #pragma unroll
;         for (int i = 0; i < 4; ++i) { ss0 += sumsq4(v0[i]); ss1 += sumsq4(v1[i]); }
;         ss0 = wave_sum(ss0); ss1 = wave_sum(ss1);
;         const float rs0 = rsqrtf(ss0 * (1.f / D) + EPS), rs1 = rsqrtf(ss1 * (1.f / D) + EPS);
; #pragma unroll
;         for (int i = 0; i < 4; ++i) {
;             xr[lane + 64 * i] = float4{v0[i].x * rs0 * gg[i].x, v0[i].y * rs0 * gg[i].y, v0[i].z * rs0 * gg[i].z, v0[i].w * rs0 * gg[i].w};
;             xr[256 + lane + 64 * i] = float4{v1[i].x * rs1 * gg[i].x, v1[i].y * rs1 * gg[i].y, v1[i].z * rs1 * gg[i].z, v1[i].w * rs1 * gg[i].w};
;         }
;     }
.LBB0_532:
	v_ashrrev_i32_e32 v51, 31, v50
	v_lshlrev_b64 v[18:19], 12, v[50:51]
	v_lshl_add_u64 v[56:57], v[52:53], 0, v[18:19]
	v_add_co_u32_e32 v54, vcc, 0x1000, v56
	global_load_dwordx4 v[30:33], v[56:57], off
	s_nop 0
	v_addc_co_u32_e32 v55, vcc, 0, v57, vcc
	global_load_dwordx4 v[38:41], v[56:57], off offset:1024
	global_load_dwordx4 v[42:45], v[56:57], off offset:2048
	global_load_dwordx4 v[46:49], v[56:57], off offset:3072
	global_load_dwordx4 v[18:21], v[54:55], off
	global_load_dwordx4 v[22:25], v[54:55], off offset:1024
	global_load_dwordx4 v[26:29], v[54:55], off offset:2048
	global_load_dwordx4 v[34:37], v[54:55], off offset:3072
	v_add_u32_e32 v50, s8, v50
	s_waitcnt vmcnt(7)
	v_pk_mul_f32 v[68:69], v[30:31], v[30:31]
	v_pk_mul_f32 v[70:71], v[32:33], v[32:33]
	s_waitcnt vmcnt(6)
	v_pk_fma_f32 v[68:69], v[38:39], v[38:39], v[68:69]
	v_pk_fma_f32 v[70:71], v[40:41], v[40:41], v[70:71]
	s_waitcnt vmcnt(5)
	v_pk_fma_f32 v[68:69], v[42:43], v[42:43], v[68:69]
	v_pk_fma_f32 v[70:71], v[44:45], v[44:45], v[70:71]
	s_waitcnt vmcnt(4)
	v_pk_fma_f32 v[68:69], v[46:47], v[46:47], v[68:69]
	v_pk_fma_f32 v[70:71], v[48:49], v[48:49], v[70:71]
	s_waitcnt vmcnt(3)
	v_pk_mul_f32 v[72:73], v[18:19], v[18:19]
	v_pk_mul_f32 v[74:75], v[20:21], v[20:21]
	s_waitcnt vmcnt(2)
	v_pk_fma_f32 v[72:73], v[22:23], v[22:23], v[72:73]
	v_pk_fma_f32 v[74:75], v[24:25], v[24:25], v[74:75]
	s_waitcnt vmcnt(1)
	v_pk_fma_f32 v[72:73], v[26:27], v[26:27], v[72:73]
	v_pk_fma_f32 v[74:75], v[28:29], v[28:29], v[74:75]
	s_waitcnt vmcnt(0)
	v_pk_fma_f32 v[72:73], v[34:35], v[34:35], v[72:73]
	v_pk_fma_f32 v[74:75], v[36:37], v[36:37], v[74:75]
	v_pk_add_f32 v[68:69], v[68:69], v[70:71]
	v_pk_add_f32 v[72:73], v[72:73], v[74:75]
	s_nop 0
	v_add_f32_e32 v59, v68, v69
	v_add_f32_e32 v58, v72, v73
	ds_bpermute_b32 v61, v62, v59
	ds_bpermute_b32 v60, v62, v58
	s_waitcnt lgkmcnt(0)
	v_pk_add_f32 v[58:59], v[58:59], v[60:61]
	ds_bpermute_b32 v61, v63, v59
	ds_bpermute_b32 v60, v63, v58
	s_waitcnt lgkmcnt(0)
	v_pk_add_f32 v[58:59], v[58:59], v[60:61]
	ds_bpermute_b32 v61, v64, v59
	ds_bpermute_b32 v60, v64, v58
	s_waitcnt lgkmcnt(0)
	v_pk_add_f32 v[58:59], v[58:59], v[60:61]
	ds_bpermute_b32 v61, v65, v59
	ds_bpermute_b32 v60, v65, v58
	s_waitcnt lgkmcnt(0)
	v_pk_add_f32 v[58:59], v[58:59], v[60:61]
	ds_bpermute_b32 v61, v66, v59
	ds_bpermute_b32 v60, v66, v58
	s_waitcnt lgkmcnt(0)
	v_pk_add_f32 v[58:59], v[58:59], v[60:61]
	ds_bpermute_b32 v61, v67, v59
	ds_bpermute_b32 v60, v67, v58
	s_waitcnt lgkmcnt(0)
	v_pk_add_f32 v[58:59], v[58:59], v[60:61]
	s_nop 0
	v_pk_fma_f32 v[58:59], v[58:59], s[96:97], v[188:189] op_sel_hi:[1,0,0]
	s_nop 0
	v_mul_f32_e32 v0, 0x4b800000, v59
	v_cmp_gt_f32_e64 s[2:3], s74, v59
	v_cmp_gt_f32_e32 vcc, s74, v58
	s_nop 0
	v_cndmask_b32_e64 v0, v59, v0, s[2:3]
	v_rsq_f32_e32 v0, v0
	s_nop 0
	v_mul_f32_e32 v51, 0x45800000, v0
	v_cndmask_b32_e64 v0, v0, v51, s[2:3]
	v_pk_mul_f32 v[30:31], v[30:31], v[0:1] op_sel_hi:[1,0]
	v_pk_mul_f32 v[32:33], v[32:33], v[0:1] op_sel_hi:[1,0]
	v_pk_mul_f32 v[30:31], v[2:3], v[30:31]
	v_pk_mul_f32 v[32:33], v[4:5], v[32:33]
	global_store_dwordx4 v[56:57], v[30:33], off nt
	s_movk_i32 s2, 0x7fff
	s_nop 0
	v_pk_mul_f32 v[30:31], v[38:39], v[0:1] op_sel_hi:[1,0]
	v_pk_mul_f32 v[32:33], v[40:41], v[0:1] op_sel_hi:[1,0]
	v_pk_mul_f32 v[30:31], v[6:7], v[30:31]
	v_pk_mul_f32 v[32:33], v[8:9], v[32:33]
	global_store_dwordx4 v[56:57], v[30:33], off offset:1024 nt
	s_nop 1
	v_pk_mul_f32 v[30:31], v[42:43], v[0:1] op_sel_hi:[1,0]
	v_pk_mul_f32 v[32:33], v[44:45], v[0:1] op_sel_hi:[1,0]
	v_pk_mul_f32 v[30:31], v[10:11], v[30:31]
	v_pk_mul_f32 v[32:33], v[12:13], v[32:33]
	global_store_dwordx4 v[56:57], v[30:33], off offset:2048 nt
	s_nop 1
	v_pk_mul_f32 v[30:31], v[46:47], v[0:1] op_sel_hi:[1,0]
	v_pk_mul_f32 v[32:33], v[48:49], v[0:1] op_sel_hi:[1,0]
	v_mul_f32_e32 v0, 0x4b800000, v58
	v_cndmask_b32_e32 v0, v58, v0, vcc
	v_rsq_f32_e32 v0, v0
	v_pk_mul_f32 v[30:31], v[14:15], v[30:31]
	v_pk_mul_f32 v[32:33], v[16:17], v[32:33]
	global_store_dwordx4 v[56:57], v[30:33], off offset:3072 nt
	s_nop 1
	v_mul_f32_e32 v30, 0x45800000, v0
	v_cndmask_b32_e32 v0, v0, v30, vcc
	v_pk_mul_f32 v[18:19], v[18:19], v[0:1] op_sel_hi:[1,0]
	v_pk_mul_f32 v[20:21], v[20:21], v[0:1] op_sel_hi:[1,0]
	v_pk_mul_f32 v[18:19], v[2:3], v[18:19]
	v_pk_mul_f32 v[20:21], v[4:5], v[20:21]
	global_store_dwordx4 v[54:55], v[18:21], off nt
	v_cmp_lt_i32_e32 vcc, s2, v50
	s_or_b64 s[6:7], vcc, s[6:7]
	v_pk_mul_f32 v[18:19], v[22:23], v[0:1] op_sel_hi:[1,0]
	v_pk_mul_f32 v[20:21], v[24:25], v[0:1] op_sel_hi:[1,0]
	v_pk_mul_f32 v[18:19], v[6:7], v[18:19]
	v_pk_mul_f32 v[20:21], v[8:9], v[20:21]
	global_store_dwordx4 v[54:55], v[18:21], off offset:1024 nt
	s_nop 1
	v_pk_mul_f32 v[18:19], v[26:27], v[0:1] op_sel_hi:[1,0]
	v_pk_mul_f32 v[20:21], v[28:29], v[0:1] op_sel_hi:[1,0]
	v_pk_mul_f32 v[18:19], v[10:11], v[18:19]
	v_pk_mul_f32 v[20:21], v[12:13], v[20:21]
	global_store_dwordx4 v[54:55], v[18:21], off offset:2048 nt
	s_nop 1
	v_pk_mul_f32 v[18:19], v[34:35], v[0:1] op_sel_hi:[1,0]
	v_pk_mul_f32 v[20:21], v[36:37], v[0:1] op_sel_hi:[1,0]
	v_pk_mul_f32 v[18:19], v[14:15], v[18:19]
	v_pk_mul_f32 v[20:21], v[16:17], v[20:21]
	global_store_dwordx4 v[54:55], v[18:21], off offset:3072 nt
	s_andn2_b64 exec, exec, s[6:7]
	s_cbranch_execnz .LBB0_532
